# P11 tail_res K loop: all 42 fragment loads in flight at once (14 register slots), reissue as consumed
# baseline (speedup 1.0000x reference)
.LBB0_1340:
	v_or_b32_e32 v0, s20, v55
	v_mad_i64_i32 v[48:49], s[20:21], v0, s14, v[34:35]
	v_or_b32_e32 v0, s19, v55
	v_mul_u32_u24_e32 v4, 0xb00, v0
	v_lshlrev_b32_e32 v4, 1, v4
	v_mov_b32_e32 v5, v33
	v_lshl_add_u64 v[104:105], v[36:37], 0, v[4:5]
	v_add_co_u32_e32 v106, vcc, s15, v104
	v_ashrrev_i32_e32 v45, 31, v44
	s_nop 0
	v_addc_co_u32_e32 v107, vcc, 0, v105, vcc
	global_load_dwordx4 v[108:111], v[48:49], off
	global_load_dwordx4 v[112:115], v[104:105], off
	global_load_dwordx4 v[116:119], v[106:107], off
	global_load_dwordx4 v[120:123], v[48:49], off offset:32
	global_load_dwordx4 v[124:127], v[104:105], off offset:32
	global_load_dwordx4 v[128:131], v[106:107], off offset:32
	global_load_dwordx4 v[132:135], v[48:49], off offset:64
	global_load_dwordx4 v[136:139], v[104:105], off offset:64
	global_load_dwordx4 v[140:143], v[106:107], off offset:64
	global_load_dwordx4 v[144:147], v[48:49], off offset:96
	global_load_dwordx4 v[148:151], v[104:105], off offset:96
	global_load_dwordx4 v[152:155], v[106:107], off offset:96
	global_load_dwordx4 v[156:159], v[48:49], off offset:128
	global_load_dwordx4 v[160:163], v[104:105], off offset:128
	global_load_dwordx4 v[164:167], v[106:107], off offset:128
	global_load_dwordx4 v[168:171], v[48:49], off offset:160
	global_load_dwordx4 v[172:175], v[104:105], off offset:160
	global_load_dwordx4 v[176:179], v[106:107], off offset:160
	global_load_dwordx4 v[180:183], v[48:49], off offset:192
	global_load_dwordx4 v[184:187], v[104:105], off offset:192
	global_load_dwordx4 v[188:191], v[106:107], off offset:192
	global_load_dwordx4 v[194:197], v[48:49], off offset:224
	global_load_dwordx4 v[198:201], v[104:105], off offset:224
	global_load_dwordx4 v[202:205], v[106:107], off offset:224
	global_load_dwordx4 v[206:209], v[48:49], off offset:256
	global_load_dwordx4 v[210:213], v[104:105], off offset:256
	global_load_dwordx4 v[214:217], v[106:107], off offset:256
	global_load_dwordx4 v[218:221], v[48:49], off offset:288
	global_load_dwordx4 v[222:225], v[104:105], off offset:288
	global_load_dwordx4 v[226:229], v[106:107], off offset:288
	global_load_dwordx4 v[230:233], v[48:49], off offset:320
	global_load_dwordx4 v[234:237], v[104:105], off offset:320
	global_load_dwordx4 v[238:241], v[106:107], off offset:320
	global_load_dwordx4 v[72:75], v[48:49], off offset:352
	global_load_dwordx4 v[76:79], v[104:105], off offset:352
	global_load_dwordx4 v[80:83], v[106:107], off offset:352
	global_load_dwordx4 v[84:87], v[48:49], off offset:384
	global_load_dwordx4 v[88:91], v[104:105], off offset:384
	global_load_dwordx4 v[92:95], v[106:107], off offset:384
	global_load_dwordx4 v[96:99], v[48:49], off offset:416
	global_load_dwordx4 v[100:103], v[104:105], off offset:416
	global_load_dwordx4 v[242:245], v[106:107], off offset:416
	v_lshlrev_b64 v[250:251], 11, v[44:45]
	v_lshl_add_u64 v[46:47], v[46:47], 0, v[250:251]
	s_nop 0
	global_load_ushort v46, v[46:47], off
	s_add_i32 s18, s18, s92
	s_add_i32 s8, s8, s9
	s_add_i32 s10, s10, s11
	s_cmpk_lt_i32 s18, 0x100
	s_waitcnt vmcnt(41)
	v_lshlrev_b32_e32 v47, 16, v71
	v_mfma_f32_32x32x16_bf16 v[16:31], v[108:111], v[112:115], 0
	s_waitcnt vmcnt(40)
	v_mfma_f32_32x32x16_bf16 v[0:15], v[108:111], v[116:119], 0
	global_load_dwordx4 v[108:111], v[48:49], off offset:448
	global_load_dwordx4 v[112:115], v[104:105], off offset:448
	global_load_dwordx4 v[116:119], v[106:107], off offset:448
	s_waitcnt vmcnt(41)
	v_mfma_f32_32x32x16_bf16 v[16:31], v[120:123], v[124:127], v[16:31]
	s_waitcnt vmcnt(40)
	v_mfma_f32_32x32x16_bf16 v[0:15], v[120:123], v[128:131], v[0:15]
	global_load_dwordx4 v[120:123], v[48:49], off offset:480
	global_load_dwordx4 v[124:127], v[104:105], off offset:480
	global_load_dwordx4 v[128:131], v[106:107], off offset:480
	s_waitcnt vmcnt(41)
	v_mfma_f32_32x32x16_bf16 v[16:31], v[132:135], v[136:139], v[16:31]
	s_waitcnt vmcnt(40)
	v_mfma_f32_32x32x16_bf16 v[0:15], v[132:135], v[140:143], v[0:15]
	global_load_dwordx4 v[132:135], v[48:49], off offset:512
	global_load_dwordx4 v[136:139], v[104:105], off offset:512
	global_load_dwordx4 v[140:143], v[106:107], off offset:512
	s_waitcnt vmcnt(41)
	v_mfma_f32_32x32x16_bf16 v[16:31], v[144:147], v[148:151], v[16:31]
	s_waitcnt vmcnt(40)
	v_mfma_f32_32x32x16_bf16 v[0:15], v[144:147], v[152:155], v[0:15]
	global_load_dwordx4 v[144:147], v[48:49], off offset:544
	global_load_dwordx4 v[148:151], v[104:105], off offset:544
	global_load_dwordx4 v[152:155], v[106:107], off offset:544
	s_waitcnt vmcnt(41)
	v_mfma_f32_32x32x16_bf16 v[16:31], v[156:159], v[160:163], v[16:31]
	s_waitcnt vmcnt(40)
	v_mfma_f32_32x32x16_bf16 v[0:15], v[156:159], v[164:167], v[0:15]
	global_load_dwordx4 v[156:159], v[48:49], off offset:576
	global_load_dwordx4 v[160:163], v[104:105], off offset:576
	global_load_dwordx4 v[164:167], v[106:107], off offset:576
	s_waitcnt vmcnt(41)
	v_mfma_f32_32x32x16_bf16 v[16:31], v[168:171], v[172:175], v[16:31]
	s_waitcnt vmcnt(40)
	v_mfma_f32_32x32x16_bf16 v[0:15], v[168:171], v[176:179], v[0:15]
	global_load_dwordx4 v[168:171], v[48:49], off offset:608
	global_load_dwordx4 v[172:175], v[104:105], off offset:608
	global_load_dwordx4 v[176:179], v[106:107], off offset:608
	s_waitcnt vmcnt(41)
	v_mfma_f32_32x32x16_bf16 v[16:31], v[180:183], v[184:187], v[16:31]
	s_waitcnt vmcnt(40)
	v_mfma_f32_32x32x16_bf16 v[0:15], v[180:183], v[188:191], v[0:15]
	global_load_dwordx4 v[180:183], v[48:49], off offset:640
	global_load_dwordx4 v[184:187], v[104:105], off offset:640
	global_load_dwordx4 v[188:191], v[106:107], off offset:640
	s_waitcnt vmcnt(41)
	v_mfma_f32_32x32x16_bf16 v[16:31], v[194:197], v[198:201], v[16:31]
	s_waitcnt vmcnt(40)
	v_mfma_f32_32x32x16_bf16 v[0:15], v[194:197], v[202:205], v[0:15]
	global_load_dwordx4 v[194:197], v[48:49], off offset:672
	global_load_dwordx4 v[198:201], v[104:105], off offset:672
	global_load_dwordx4 v[202:205], v[106:107], off offset:672
	s_waitcnt vmcnt(41)
	v_mfma_f32_32x32x16_bf16 v[16:31], v[206:209], v[210:213], v[16:31]
	s_waitcnt vmcnt(40)
	v_mfma_f32_32x32x16_bf16 v[0:15], v[206:209], v[214:217], v[0:15]
	s_waitcnt vmcnt(38)
	v_mfma_f32_32x32x16_bf16 v[16:31], v[218:221], v[222:225], v[16:31]
	s_waitcnt vmcnt(37)
	v_mfma_f32_32x32x16_bf16 v[0:15], v[218:221], v[226:229], v[0:15]
	s_waitcnt vmcnt(35)
	v_mfma_f32_32x32x16_bf16 v[16:31], v[230:233], v[234:237], v[16:31]
	s_waitcnt vmcnt(34)
	v_mfma_f32_32x32x16_bf16 v[0:15], v[230:233], v[238:241], v[0:15]
	s_waitcnt vmcnt(32)
	v_mfma_f32_32x32x16_bf16 v[16:31], v[72:75], v[76:79], v[16:31]
	s_waitcnt vmcnt(31)
	v_mfma_f32_32x32x16_bf16 v[0:15], v[72:75], v[80:83], v[0:15]
	s_waitcnt vmcnt(29)
	v_mfma_f32_32x32x16_bf16 v[16:31], v[84:87], v[88:91], v[16:31]
	s_waitcnt vmcnt(28)
	v_mfma_f32_32x32x16_bf16 v[0:15], v[84:87], v[92:95], v[0:15]
	s_waitcnt vmcnt(26)
	v_mfma_f32_32x32x16_bf16 v[16:31], v[96:99], v[100:103], v[16:31]
	s_waitcnt vmcnt(25)
	v_mfma_f32_32x32x16_bf16 v[0:15], v[96:99], v[242:245], v[0:15]
	s_waitcnt vmcnt(22)
	v_mfma_f32_32x32x16_bf16 v[16:31], v[108:111], v[112:115], v[16:31]
	s_waitcnt vmcnt(21)
	v_mfma_f32_32x32x16_bf16 v[0:15], v[108:111], v[116:119], v[0:15]
	s_waitcnt vmcnt(19)
	v_mfma_f32_32x32x16_bf16 v[16:31], v[120:123], v[124:127], v[16:31]
	s_waitcnt vmcnt(18)
	v_mfma_f32_32x32x16_bf16 v[0:15], v[120:123], v[128:131], v[0:15]
	s_waitcnt vmcnt(16)
	v_mfma_f32_32x32x16_bf16 v[16:31], v[132:135], v[136:139], v[16:31]
	s_waitcnt vmcnt(15)
	v_mfma_f32_32x32x16_bf16 v[0:15], v[132:135], v[140:143], v[0:15]
	s_waitcnt vmcnt(13)
	v_mfma_f32_32x32x16_bf16 v[16:31], v[144:147], v[148:151], v[16:31]
	s_waitcnt vmcnt(12)
	v_mfma_f32_32x32x16_bf16 v[0:15], v[144:147], v[152:155], v[0:15]
	s_waitcnt vmcnt(10)
	v_mfma_f32_32x32x16_bf16 v[16:31], v[156:159], v[160:163], v[16:31]
	s_waitcnt vmcnt(9)
	v_mfma_f32_32x32x16_bf16 v[0:15], v[156:159], v[164:167], v[0:15]
	s_waitcnt vmcnt(7)
	v_mfma_f32_32x32x16_bf16 v[16:31], v[168:171], v[172:175], v[16:31]
	s_waitcnt vmcnt(6)
	v_mfma_f32_32x32x16_bf16 v[0:15], v[168:171], v[176:179], v[0:15]
	s_waitcnt vmcnt(4)
	v_mfma_f32_32x32x16_bf16 v[16:31], v[180:183], v[184:187], v[16:31]
	s_waitcnt vmcnt(3)
	v_mfma_f32_32x32x16_bf16 v[0:15], v[180:183], v[188:191], v[0:15]
	s_waitcnt vmcnt(1)
	v_mfma_f32_32x32x16_bf16 v[16:31], v[194:197], v[198:201], v[16:31]
	s_waitcnt vmcnt(0)
	v_mfma_f32_32x32x16_bf16 v[0:15], v[194:197], v[202:205], v[0:15]
	s_nop 9
	ds_write2st64_b32 v56, v16, v17 offset1:1
	ds_write2st64_b32 v56, v18, v19 offset0:2 offset1:3
	ds_write2st64_b32 v56, v20, v21 offset0:4 offset1:5
	ds_write2st64_b32 v56, v22, v23 offset0:6 offset1:7
	ds_write2st64_b32 v56, v24, v25 offset0:8 offset1:9
	ds_write2st64_b32 v56, v26, v27 offset0:10 offset1:11
	ds_write2st64_b32 v56, v28, v29 offset0:12 offset1:13
	ds_write2st64_b32 v56, v30, v31 offset0:14 offset1:15
	ds_write2st64_b32 v56, v0, v1 offset0:16 offset1:17
	ds_write2st64_b32 v56, v2, v3 offset0:18 offset1:19
	ds_write2st64_b32 v56, v4, v5 offset0:20 offset1:21
	ds_write2st64_b32 v56, v6, v7 offset0:22 offset1:23
	ds_write2st64_b32 v56, v8, v9 offset0:24 offset1:25
	ds_write2st64_b32 v56, v10, v11 offset0:26 offset1:27
	ds_write2st64_b32 v56, v12, v13 offset0:28 offset1:29
	ds_write2st64_b32 v56, v14, v15 offset0:30 offset1:31
	s_waitcnt lgkmcnt(0)
	s_barrier
	ds_read2st64_b32 v[0:1], v57 offset1:32
	ds_read2st64_b32 v[2:3], v57 offset0:64 offset1:96
	ds_read2st64_b32 v[4:5], v57 offset0:128 offset1:160
	v_lshlrev_b32_e32 v7, 16, v69
	v_lshlrev_b32_e32 v6, 16, v70
	s_waitcnt lgkmcnt(2)
	v_add_f32_e32 v0, 0, v0
	v_add_f32_e32 v0, v0, v1
	s_waitcnt lgkmcnt(1)
	v_add_f32_e32 v2, v0, v2
	ds_read2st64_b32 v[0:1], v57 offset0:192 offset1:224
	v_add_f32_e32 v2, v2, v3
	s_waitcnt lgkmcnt(1)
	v_add_f32_e32 v4, v2, v4
	ds_read2st64_b32 v[2:3], v58 offset1:32
	v_add_f32_e32 v4, v4, v5
	s_waitcnt lgkmcnt(1)
	v_add_f32_e32 v0, v4, v0
	ds_read2st64_b32 v[4:5], v58 offset0:64 offset1:96
	v_add_f32_e32 v9, v0, v1
	s_waitcnt lgkmcnt(1)
	v_add_f32_e32 v2, 0, v2
	ds_read2st64_b32 v[0:1], v58 offset0:128 offset1:160
	v_add_f32_e32 v2, v2, v3
	s_waitcnt lgkmcnt(1)
	v_add_f32_e32 v4, v2, v4
	ds_read2st64_b32 v[2:3], v58 offset0:192 offset1:224
	v_add_f32_e32 v4, v4, v5
	s_waitcnt lgkmcnt(1)
	v_add_f32_e32 v0, v4, v0
	ds_read2st64_b32 v[4:5], v59 offset1:32
	v_add_f32_e32 v0, v0, v1
	s_waitcnt lgkmcnt(1)
	v_add_f32_e32 v2, v0, v2
	ds_read2st64_b32 v[0:1], v59 offset0:64 offset1:96
	v_add_f32_e32 v10, v2, v3
	s_waitcnt lgkmcnt(1)
	v_add_f32_e32 v4, 0, v4
	ds_read2st64_b32 v[2:3], v59 offset0:128 offset1:160
	v_add_f32_e32 v4, v4, v5
	s_waitcnt lgkmcnt(1)
	v_add_f32_e32 v0, v4, v0
	ds_read2st64_b32 v[4:5], v59 offset0:192 offset1:224
	v_add_f32_e32 v0, v0, v1
	s_waitcnt lgkmcnt(1)
	v_add_f32_e32 v2, v0, v2
	ds_read2st64_b32 v[0:1], v60 offset1:32
	v_add_f32_e32 v2, v2, v3
	s_waitcnt lgkmcnt(1)
	v_add_f32_e32 v2, v2, v4
	v_add_f32_e32 v11, v2, v5
	ds_read2st64_b32 v[2:3], v60 offset0:64 offset1:96
	ds_read2st64_b32 v[4:5], v60 offset0:128 offset1:160
	s_waitcnt lgkmcnt(2)
	v_add_f32_e32 v0, 0, v0
	v_add_f32_e32 v12, v0, v1
	ds_read2st64_b32 v[0:1], v60 offset0:192 offset1:224
	s_waitcnt lgkmcnt(2)
	v_add_f32_e32 v2, v12, v2
	v_add_f32_e32 v2, v2, v3
	s_waitcnt lgkmcnt(1)
	v_add_f32_e32 v2, v2, v4
	v_add_f32_e32 v2, v2, v5
	s_waitcnt lgkmcnt(0)
	v_add_f32_e32 v0, v2, v0
	v_add_f32_e32 v2, v0, v1
	v_add_f32_e32 v0, v62, v9
	v_mul_f32_e32 v3, v61, v0
	v_lshlrev_b64 v[0:1], 12, v[38:39]
	v_lshl_add_u64 v[0:1], s[22:23], 0, v[0:1]
	v_fmac_f32_e32 v3, 0x3f9837f0, v7
	v_lshl_add_u64 v[0:1], v[0:1], 0, v[32:33]
	s_barrier
	global_store_dword v[0:1], v3, off
	v_add_f32_e32 v0, v65, v10
	v_mul_f32_e32 v3, v64, v0
	v_lshlrev_b64 v[0:1], 12, v[40:41]
	v_lshl_add_u64 v[0:1], s[22:23], 0, v[0:1]
	v_fmac_f32_e32 v3, 0x3f9837f0, v6
	v_lshl_add_u64 v[0:1], v[0:1], 0, v[32:33]
	global_store_dword v[0:1], v3, off
	v_add_f32_e32 v0, v63, v11
	v_mul_f32_e32 v3, v66, v0
	v_lshlrev_b64 v[0:1], 12, v[42:43]
	v_lshl_add_u64 v[0:1], s[22:23], 0, v[0:1]
	v_fmac_f32_e32 v3, 0x3f9837f0, v47
	v_lshl_add_u64 v[0:1], v[0:1], 0, v[32:33]
	global_store_dword v[0:1], v3, off
	v_add_f32_e32 v0, v68, v2
	v_mul_f32_e32 v2, v67, v0
	v_lshlrev_b64 v[0:1], 12, v[44:45]
	v_lshlrev_b32_e32 v8, 16, v46
	v_lshl_add_u64 v[0:1], s[22:23], 0, v[0:1]
	v_fmac_f32_e32 v2, 0x3f9837f0, v8
	v_lshl_add_u64 v[0:1], v[0:1], 0, v[32:33]
	global_store_dword v[0:1], v2, off
	s_cbranch_scc0 .LBB0_1349
